# v7 + gate/up GEMM epilogue (silu*up, 64 values per lane) renamed into free fragment registers and list-scheduled so the exp/rcp chains of different elements overlap
# speedup vs baseline: 1.0088x; 1.0025x over previous
; __device__ __forceinline__ unsigned cvtpk(float lo, float hi) { unsigned r; asm volatile("v_cvt_pk_bf16_f32 %0, %1, %2" : "=v"(r) : "v"(lo), "v"(hi)); return r; }
; __device__ __forceinline__ float sigmoidf_(float x) { return __builtin_amdgcn_rcpf(1.f + __builtin_amdgcn_exp2f(x * -1.4426950408889634f)); }
;   __device__ __forceinline__ void operator()(const Acc& acc, const gm::Unit& u, int wr, int wc, int fr, int fq) const {
;     bf16_t* dst = ACT + ((size_t)(u.pm * 44 + u.pn) * 256) * 128 + wc * 32 + fq * 8;
; #pragma unroll
;     for (int ai = 0; ai < 2; ++ai)
; #pragma unroll
;       for (int m = 0; m < 4; ++m) { bf16_t* dr = dst + (size_t)(ai * 128 + wr * 64 + m * 16 + fr) * 128; u32x4 w;
; #pragma unroll
;         for (int n = 0; n < 2; ++n) { const f32x4 g = acc[ai][0][m][n], uu = acc[ai][1][m][n];
;           w[2 * n] = cvtpk(g[0] * sigmoidf_(g[0]) * uu[0], g[1] * sigmoidf_(g[1]) * uu[1]); w[2 * n + 1] = cvtpk(g[2] * sigmoidf_(g[2]) * uu[2], g[3] * sigmoidf_(g[3]) * uu[3]); }
;         *(u32x4*)dr = w; }
;   }
.LBB0_1130:
	v_mul_f32_e32 v154, 0xbfb8aa3b, v126
	v_exp_f32_e32 v155, v154
	v_mul_f32_e32 v159, 0xbfb8aa3b, v127
	v_exp_f32_e32 v160, v159
	v_mul_f32_e32 v170, 0xbfb8aa3b, v129
	v_mov_b32_e32 v153, v1
	v_exp_f32_e32 v171, v170
	v_add_u32_e32 v144, s44, v153
	v_ashrrev_i32_e32 v145, 31, v144
	v_lshlrev_b64 v[150:151], 8, v[144:145]
	v_add_f32_e32 v156, 1.0, v155
	v_mul_f32_e32 v176, 0xbfb8aa3b, v118
	v_rcp_f32_e32 v145, v156
	v_add_f32_e32 v161, 1.0, v160
	v_exp_f32_e32 v177, v176
	v_mul_f32_e32 v187, 0xbfb8aa3b, v120
	v_rcp_f32_e32 v162, v161
	v_exp_f32_e32 v188, v187
	v_add_f32_e32 v172, 1.0, v171
	v_rcp_f32_e32 v173, v172
	v_mul_f32_e32 v157, v126, v145
	v_add_f32_e32 v178, 1.0, v177
	v_mul_f32_e32 v126, v127, v162
	v_rcp_f32_e32 v179, v178
	v_add_f32_e32 v191, 1.0, v188
	v_mul_f32_e32 v158, v157, v122
	v_mul_f32_e32 v163, v126, v123
	v_rcp_f32_e32 v192, v191
	v_mul_f32_e32 v196, 0xbfb8aa3b, v110
	v_cvt_pk_bf16_f32 v122, v158, v163
	v_mul_f32_e32 v174, v129, v173
	v_exp_f32_e32 v197, v196
	v_mul_f32_e32 v202, 0xbfb8aa3b, v111
	v_mul_f32_e32 v162, 0xbfb8aa3b, v102
	v_mov_b32_e32 v152, v146
	v_mul_f32_e32 v164, 0xbfb8aa3b, v128
	v_mul_f32_e32 v175, v174, v125
	v_mul_f32_e32 v182, 0xbfb8aa3b, v119
	v_exp_f32_e32 v203, v202
	v_exp_f32_e32 v158, v162
	v_mul_f32_e32 v173, 0xbfb8aa3b, v104
	v_lshlrev_b32_e32 v142, 3, v152
	v_exp_f32_e32 v165, v164
	v_exp_f32_e32 v183, v182
	v_mul_f32_e32 v156, 0xbfb8aa3b, v113
	v_exp_f32_e32 v174, v173
	v_exp_f32_e32 v152, v156
	v_mul_f32_e32 v180, v118, v179
	v_mul_f32_e32 v189, 0xbfb8aa3b, v121
	v_mul_f32_e32 v181, v180, v114
	v_exp_f32_e32 v190, v189
	v_mul_f32_e32 v195, v120, v192
	v_mul_f32_e32 v114, v195, v116
	v_add_f32_e32 v199, 1.0, v197
	v_rcp_f32_e32 v116, v199
	v_add_f32_e32 v204, 1.0, v203
	v_add_f32_e32 v163, 1.0, v158
	v_add_f32_e32 v166, 1.0, v165
	v_add_f32_e32 v184, 1.0, v183
	v_rcp_f32_e32 v205, v204
	v_rcp_f32_e32 v164, v163
	v_add_f32_e32 v176, 1.0, v174
	v_rcp_f32_e32 v167, v166
	v_rcp_f32_e32 v185, v184
	v_add_f32_e32 v157, 1.0, v152
	v_rcp_f32_e32 v177, v176
	v_mul_f32_e32 v182, 0xbfb8aa3b, v94
	v_rcp_f32_e32 v159, v157
	v_exp_f32_e32 v183, v182
	v_mul_f32_e32 v187, 0xbfb8aa3b, v95
	v_exp_f32_e32 v189, v187
	v_mul_f32_e32 v207, 0xbfb8aa3b, v112
	v_mul_f32_e32 v197, 0xbfb8aa3b, v97
	v_mul_f32_e32 v200, v110, v116
	v_exp_f32_e32 v208, v207
	v_exp_f32_e32 v199, v197
	v_mul_f32_e32 v110, v111, v205
	v_mul_f32_e32 v165, v102, v164
	v_mul_f32_e32 v118, v119, v185
	v_mul_f32_e32 v201, v200, v106
	v_mul_f32_e32 v206, v110, v107
	v_mul_f32_e32 v166, v165, v98
	v_mul_f32_e32 v180, v104, v177
	v_mul_f32_e32 v168, v128, v167
	v_cvt_pk_bf16_f32 v106, v201, v206
	v_mul_f32_e32 v160, v113, v159
	v_mul_f32_e32 v98, v180, v100
	v_add_f32_e32 v185, 1.0, v183
	v_mul_f32_e32 v205, 0xbfb8aa3b, v86
	v_mul_f32_e32 v169, v168, v124
	v_mul_f32_e32 v161, v160, v109
	v_mul_f32_e32 v167, 0xbfb8aa3b, v103
	v_rcp_f32_e32 v100, v185
	v_add_f32_e32 v188, 1.0, v189
	v_exp_f32_e32 v201, v205
	v_mul_f32_e32 v159, 0xbfb8aa3b, v88
	v_cvt_pk_bf16_f32 v123, v169, v175
	v_exp_f32_e32 v168, v167
	v_rcp_f32_e32 v191, v188
	v_exp_f32_e32 v160, v159
	v_add_f32_e32 v209, 1.0, v208
	v_mul_f32_e32 v169, 0xbfb8aa3b, v105
	v_add_f32_e32 v200, 1.0, v199
	v_add_f32_e32 v193, 1.0, v190
	v_rcp_f32_e32 v153, v209
	v_exp_f32_e32 v175, v169
	v_rcp_f32_e32 v202, v200
	v_mul_f32_e32 v186, v118, v115
	v_rcp_f32_e32 v194, v193
	v_cvt_pk_bf16_f32 v124, v181, v186
	v_mul_f32_e32 v181, v94, v100
	v_add_f32_e32 v206, 1.0, v201
	v_add_f32_e32 v170, 1.0, v168
	v_mul_f32_e32 v94, v95, v191
	v_rcp_f32_e32 v207, v206
	v_add_f32_e32 v162, 1.0, v160
	v_rcp_f32_e32 v171, v170
	v_mul_f32_e32 v186, v181, v90
	v_mul_f32_e32 v190, v94, v91
	v_rcp_f32_e32 v158, v162
	v_mul_f32_e32 v167, 0xbfb8aa3b, v78
	v_mul_f32_e32 v154, v112, v153
	v_add_f32_e32 v178, 1.0, v175
	v_cvt_pk_bf16_f32 v90, v186, v190
	v_mul_f32_e32 v203, v97, v202
	v_exp_f32_e32 v168, v167
	v_mul_f32_e32 v173, 0xbfb8aa3b, v79
	v_mul_f32_e32 v191, 0xbfb8aa3b, v70
	v_mul_f32_e32 v155, v154, v108
	v_rcp_f32_e32 v179, v178
	v_mul_f32_e32 v193, 0xbfb8aa3b, v96
	v_mul_f32_e32 v204, v203, v93
	v_mul_f32_e32 v153, 0xbfb8aa3b, v87
	v_exp_f32_e32 v169, v173
	v_exp_f32_e32 v186, v191
	v_mul_f32_e32 v202, 0xbfb8aa3b, v72
	v_exp_f32_e32 v192, v193
	v_exp_f32_e32 v154, v153
	v_mul_f32_e32 v183, 0xbfb8aa3b, v81
	v_exp_f32_e32 v203, v202
	v_cvt_pk_bf16_f32 v107, v155, v161
	v_exp_f32_e32 v185, v183
	v_mul_f32_e32 v208, v86, v207
	v_mul_f32_e32 v155, 0xbfb8aa3b, v89
	v_mul_f32_e32 v102, v103, v171
	v_mul_f32_e32 v209, v208, v82
	v_exp_f32_e32 v161, v155
	v_mul_f32_e32 v165, v88, v158
	v_mul_f32_e32 v82, v165, v84
	v_add_f32_e32 v171, 1.0, v168
	v_rcp_f32_e32 v84, v171
	v_add_f32_e32 v174, 1.0, v169
	v_mul_f32_e32 v178, 0xbfb8aa3b, v80
	v_add_f32_e32 v190, 1.0, v186
	v_add_f32_e32 v195, 1.0, v192
	v_add_f32_e32 v156, 1.0, v154
	v_rcp_f32_e32 v176, v174
	v_exp_f32_e32 v177, v178
	v_rcp_f32_e32 v193, v190
	v_add_f32_e32 v205, 1.0, v203
	v_rcp_f32_e32 v196, v195
	v_rcp_f32_e32 v152, v156
	v_add_f32_e32 v181, 1.0, v185
	v_rcp_f32_e32 v201, v205
	v_mul_f32_e32 v153, 0xbfb8aa3b, v62
	v_rcp_f32_e32 v187, v181
	v_exp_f32_e32 v154, v153
	v_mul_f32_e32 v159, 0xbfb8aa3b, v63
	v_mul_f32_e32 v172, v102, v99
	v_exp_f32_e32 v155, v159
	v_cvt_pk_bf16_f32 v108, v166, v172
	v_mul_f32_e32 v168, 0xbfb8aa3b, v65
	v_mul_f32_e32 v166, v78, v84
	v_exp_f32_e32 v171, v168
	v_mul_f32_e32 v198, v121, v194
	v_mul_f32_e32 v78, v79, v176
	v_add_f32_e32 v180, 1.0, v177
	v_mul_f32_e32 v192, v70, v193
	v_mul_f32_e32 v115, v198, v117
	v_mul_f32_e32 v194, v96, v196
	v_mul_f32_e32 v86, v87, v152
	v_mul_f32_e32 v172, v166, v74
	v_mul_f32_e32 v175, v78, v75
; __device__ __forceinline__ unsigned cvtpk(float lo, float hi) { unsigned r; asm volatile("v_cvt_pk_bf16_f32 %0, %1, %2" : "=v"(r) : "v"(lo), "v"(hi)); return r; }
; __device__ __forceinline__ float sigmoidf_(float x) { return __builtin_amdgcn_rcpf(1.f + __builtin_amdgcn_exp2f(x * -1.4426950408889634f)); }
;   __device__ __forceinline__ void operator()(const Acc& acc, const gm::Unit& u, int wr, int wc, int fr, int fq) const {
;     bf16_t* dst = ACT + ((size_t)(u.pm * 44 + u.pn) * 256) * 128 + wc * 32 + fq * 8;
; #pragma unroll
;     for (int ai = 0; ai < 2; ++ai)
; #pragma unroll
;       for (int m = 0; m < 4; ++m) { bf16_t* dr = dst + (size_t)(ai * 128 + wr * 64 + m * 16 + fr) * 128; u32x4 w;
; #pragma unroll
;         for (int n = 0; n < 2; ++n) { const f32x4 g = acc[ai][0][m][n], uu = acc[ai][1][m][n];
;           w[2 * n] = cvtpk(g[0] * sigmoidf_(g[0]) * uu[0], g[1] * sigmoidf_(g[1]) * uu[1]); w[2 * n + 1] = cvtpk(g[2] * sigmoidf_(g[2]) * uu[2], g[3] * sigmoidf_(g[3]) * uu[3]); }
;         *(u32x4*)dr = w; }
;   }
	v_rcp_f32_e32 v182, v180
	v_mul_f32_e32 v195, v192, v66
	v_mul_f32_e32 v208, v72, v201
	v_mul_f32_e32 v198, v194, v92
	v_cvt_pk_bf16_f32 v74, v172, v175
	v_mul_f32_e32 v189, v81, v187
	v_mul_f32_e32 v66, v208, v68
	v_add_f32_e32 v152, 1.0, v154
	v_mul_f32_e32 v176, 0xbfb8aa3b, v54
	v_cvt_pk_bf16_f32 v91, v198, v204
	v_add_f32_e32 v163, 1.0, v161
	v_mul_f32_e32 v188, v189, v77
	v_mul_f32_e32 v196, 0xbfb8aa3b, v71
	v_rcp_f32_e32 v68, v152
	v_add_f32_e32 v160, 1.0, v155
	v_exp_f32_e32 v172, v176
	v_mul_f32_e32 v187, 0xbfb8aa3b, v56
	v_rcp_f32_e32 v164, v163
	v_exp_f32_e32 v194, v196
	v_mul_f32_e32 v198, 0xbfb8aa3b, v73
	v_rcp_f32_e32 v162, v160
	v_exp_f32_e32 v189, v187
	v_exp_f32_e32 v204, v198
	v_add_f32_e32 v166, 1.0, v171
	v_mul_f32_e32 v184, v105, v179
	v_rcp_f32_e32 v173, v166
	v_mul_f32_e32 v99, v184, v101
	v_mul_f32_e32 v157, v86, v83
	v_mul_f32_e32 v179, v80, v182
	v_cvt_pk_bf16_f32 v92, v209, v157
	v_mul_f32_e32 v184, v179, v76
	v_cvt_pk_bf16_f32 v75, v184, v188
	v_mul_f32_e32 v209, v62, v68
	v_add_f32_e32 v175, 1.0, v172
	v_add_f32_e32 v197, 1.0, v194
	v_mul_f32_e32 v62, v63, v162
	v_mul_f32_e32 v163, 0xbfb8aa3b, v64
	v_rcp_f32_e32 v178, v175
	v_mul_f32_e32 v184, 0xbfb8aa3b, v57
	v_add_f32_e32 v191, 1.0, v189
	v_rcp_f32_e32 v199, v197
	v_add_f32_e32 v206, 1.0, v204
	v_mul_f32_e32 v157, v209, v58
	v_mul_f32_e32 v161, v62, v59
	v_exp_f32_e32 v158, v163
	v_exp_f32_e32 v188, v184
	v_rcp_f32_e32 v186, v191
	v_mul_f32_e32 v196, 0xbfb8aa3b, v46
	v_rcp_f32_e32 v207, v206
	v_cvt_pk_bf16_f32 v58, v157, v161
	v_mul_f32_e32 v169, v65, v173
	v_exp_f32_e32 v194, v196
	v_mul_f32_e32 v162, 0xbfb8aa3b, v38
	v_mul_f32_e32 v174, v169, v61
	v_mul_f32_e32 v182, 0xbfb8aa3b, v55
	v_exp_f32_e32 v157, v162
	v_mul_f32_e32 v173, 0xbfb8aa3b, v40
	v_exp_f32_e32 v179, v182
	v_exp_f32_e32 v169, v173
	s_mul_i32 s0, s60, 44
	v_mul_f32_e32 v202, 0xbfb8aa3b, v47
	s_add_i32 s0, s0, s62
	v_mul_f32_e32 v177, v54, v178
	v_exp_f32_e32 v198, v202
	s_ashr_i32 s1, s0, 31
	v_mul_f32_e32 v70, v71, v199
	v_add_f32_e32 v165, 1.0, v158
	v_mul_f32_e32 v180, v177, v50
	v_add_f32_e32 v190, 1.0, v188
	v_mul_f32_e32 v192, v56, v186
	v_mul_f32_e32 v154, 0xbfb8aa3b, v49
	s_lshl_b64 s[0:1], s[0:1], 16
	v_rcp_f32_e32 v167, v165
	v_rcp_f32_e32 v193, v190
	v_mul_f32_e32 v50, v192, v52
	v_add_f32_e32 v199, 1.0, v194
	v_mul_f32_e32 v206, 0xbfb8aa3b, v48
	v_exp_f32_e32 v152, v154
	s_add_u32 s0, s70, s0
	v_rcp_f32_e32 v52, v199
	v_exp_f32_e32 v201, v206
	v_add_f32_e32 v161, 1.0, v157
	s_addc_u32 s1, s71, s1
	v_ashrrev_i32_e32 v143, 31, v142
	v_add_f32_e32 v183, 1.0, v179
	v_rcp_f32_e32 v163, v161
	v_add_f32_e32 v176, 1.0, v169
	v_lshl_add_u64 v[142:143], v[142:143], 1, s[0:1]
	v_cvt_pk_bf16_f32 v125, v114, v115
	v_rcp_f32_e32 v185, v183
	v_rcp_f32_e32 v172, v176
	v_mul_f32_e32 v182, 0xbfb8aa3b, v30
	v_lshl_add_u64 v[114:115], v[142:143], 0, v[150:151]
	v_add_f32_e32 v203, 1.0, v198
	v_exp_f32_e32 v179, v182
	v_mul_f32_e32 v187, 0xbfb8aa3b, v31
	global_store_dwordx4 v[114:115], v[122:125], off
	v_mul_f32_e32 v170, v89, v164
	v_rcp_f32_e32 v205, v203
	v_exp_f32_e32 v184, v187
	v_add_u32_e32 v114, 16, v144
	v_mul_f32_e32 v83, v170, v85
	v_mul_f32_e32 v164, v64, v167
	v_add_f32_e32 v209, 1.0, v152
	v_mul_f32_e32 v190, 0xbfb8aa3b, v32
	v_mul_f32_e32 v194, 0xbfb8aa3b, v33
	v_ashrrev_i32_e32 v115, 31, v114
	v_mul_f32_e32 v170, v164, v60
	v_add_f32_e32 v208, 1.0, v201
	v_rcp_f32_e32 v159, v209
	v_exp_f32_e32 v186, v190
	v_exp_f32_e32 v199, v194
	v_lshlrev_b64 v[114:115], 8, v[114:115]
	v_cvt_pk_bf16_f32 v109, v98, v99
	v_mul_f32_e32 v200, v70, v67
	v_cvt_pk_bf16_f32 v59, v170, v174
	v_rcp_f32_e32 v153, v208
	v_mul_f32_e32 v158, v38, v163
	v_lshl_add_u64 v[98:99], v[142:143], 0, v[114:115]
	v_cvt_pk_bf16_f32 v76, v195, v200
	v_mul_f32_e32 v54, v55, v185
	v_mul_f32_e32 v165, v158, v34
	v_mul_f32_e32 v170, 0xbfb8aa3b, v41
	v_mul_f32_e32 v177, v40, v172
	global_store_dwordx4 v[98:99], v[106:109], off
	v_mul_f32_e32 v195, v46, v52
	v_exp_f32_e32 v174, v170
	v_mul_f32_e32 v34, v177, v36
	v_add_f32_e32 v185, 1.0, v179
	v_add_u32_e32 v98, 32, v144
	v_mul_f32_e32 v46, v47, v205
	v_mul_f32_e32 v167, 0xbfb8aa3b, v39
	v_rcp_f32_e32 v36, v185
	v_add_f32_e32 v189, 1.0, v184
	v_ashrrev_i32_e32 v99, 31, v98
	v_mul_f32_e32 v200, v195, v42
	v_mul_f32_e32 v204, v46, v43
	v_exp_f32_e32 v164, v167
	v_rcp_f32_e32 v191, v189
	v_lshlrev_b64 v[98:99], 8, v[98:99]
	v_cvt_pk_bf16_f32 v93, v82, v83
	v_mul_f32_e32 v156, v73, v207
	v_cvt_pk_bf16_f32 v42, v200, v204
	v_mul_f32_e32 v155, v49, v159
	v_add_f32_e32 v192, 1.0, v186
	v_add_f32_e32 v195, 1.0, v199
	v_mul_f32_e32 v205, 0xbfb8aa3b, v22
; __device__ __forceinline__ unsigned cvtpk(float lo, float hi) { unsigned r; asm volatile("v_cvt_pk_bf16_f32 %0, %1, %2" : "=v"(r) : "v"(lo), "v"(hi)); return r; }
; __device__ __forceinline__ float sigmoidf_(float x) { return __builtin_amdgcn_rcpf(1.f + __builtin_amdgcn_exp2f(x * -1.4426950408889634f)); }
; #define PG8_BAR __builtin_amdgcn_s_barrier()
;     ...
;     if (!has_next) break;
; #pragma unroll
;     for (int a = 0; a < 2; ++a)
; #pragma unroll
;       for (int b = 0; b < 2; ++b)
; #pragma unroll
;         for (int m = 0; m < 4; ++m)
; #pragma unroll
;           for (int n = 0; n < 2; ++n) acc[a][b][m][n] = (f32x4){0.f, 0.f, 0.f, 0.f};
;     cur = nxt; cA = nA; cB = nB; ++ui;
;     if (wr == 1) PG8_BAR;
;   __device__ __forceinline__ void operator()(const Acc& acc, const gm::Unit& u, int wr, int wc, int fr, int fq) const {
;     ...
;       for (int m = 0; m < 4; ++m) { bf16_t* dr = dst + (size_t)(ai * 128 + wr * 64 + m * 16 + fr) * 128; u32x4 w;
; #pragma unroll
;         for (int n = 0; n < 2; ++n) { const f32x4 g = acc[ai][0][m][n], uu = acc[ai][1][m][n];
;           w[2 * n] = cvtpk(g[0] * sigmoidf_(g[0]) * uu[0], g[1] * sigmoidf_(g[1]) * uu[1]); w[2 * n + 1] = cvtpk(g[2] * sigmoidf_(g[2]) * uu[2], g[3] * sigmoidf_(g[3]) * uu[3]); }
;         *(u32x4*)dr = w; }
	v_lshl_add_u64 v[82:83], v[142:143], 0, v[98:99]
	v_mul_f32_e32 v67, v156, v69
	v_mul_f32_e32 v207, v48, v153
	v_mul_f32_e32 v160, v155, v45
	v_rcp_f32_e32 v196, v192
	v_rcp_f32_e32 v202, v195
	v_exp_f32_e32 v200, v205
	v_mul_f32_e32 v159, 0xbfb8aa3b, v24
	global_store_dwordx4 v[82:83], v[90:93], off
	v_mul_f32_e32 v181, v54, v51
	v_mul_f32_e32 v156, v207, v44
	v_exp_f32_e32 v155, v159
	v_add_u32_e32 v82, 48, v144
	v_cvt_pk_bf16_f32 v60, v180, v181
	v_cvt_pk_bf16_f32 v43, v156, v160
	v_add_f32_e32 v175, 1.0, v174
	v_mul_f32_e32 v153, 0xbfb8aa3b, v23
	v_ashrrev_i32_e32 v83, 31, v82
	v_rcp_f32_e32 v178, v175
	v_mul_f32_e32 v180, v30, v36
	v_exp_f32_e32 v207, v153
	v_mul_f32_e32 v156, 0xbfb8aa3b, v25
	v_lshlrev_b64 v[82:83], 8, v[82:83]
	v_cvt_pk_bf16_f32 v77, v66, v67
	v_add_f32_e32 v168, 1.0, v164
	v_mul_f32_e32 v30, v31, v191
	v_exp_f32_e32 v160, v156
	v_lshl_add_u64 v[66:67], v[142:143], 0, v[82:83]
	v_mul_f32_e32 v197, v57, v193
	v_rcp_f32_e32 v171, v168
	v_mul_f32_e32 v181, v180, v26
	v_mul_f32_e32 v188, v30, v27
	global_store_dwordx4 v[66:67], v[74:77], off
	v_mul_f32_e32 v51, v197, v53
	v_cvt_pk_bf16_f32 v26, v181, v188
	v_mul_f32_e32 v193, v32, v196
	v_mul_f32_e32 v198, v33, v202
	v_add_f32_e32 v204, 1.0, v200
	v_mul_f32_e32 v191, 0xbfb8aa3b, v6
	v_add_u32_e32 v66, 0x80, v144
	v_mul_f32_e32 v197, v193, v28
	v_mul_f32_e32 v203, v198, v29
	v_rcp_f32_e32 v206, v204
	v_add_f32_e32 v162, 1.0, v155
	v_exp_f32_e32 v181, v191
	v_mul_f32_e32 v196, 0xbfb8aa3b, v7
	v_ashrrev_i32_e32 v67, 31, v66
	v_cvt_pk_bf16_f32 v27, v197, v203
	v_rcp_f32_e32 v157, v162
	v_mul_f32_e32 v167, 0xbfb8aa3b, v14
	v_mul_f32_e32 v179, 0xbfb8aa3b, v17
	v_exp_f32_e32 v193, v196
	v_mul_f32_e32 v202, 0xbfb8aa3b, v8
	v_mul_f32_e32 v198, 0xbfb8aa3b, v9
	v_lshlrev_b64 v[66:67], 8, v[66:67]
	v_cvt_pk_bf16_f32 v61, v50, v51
	v_add_f32_e32 v154, 1.0, v207
	v_exp_f32_e32 v164, v167
	v_mul_f32_e32 v173, 0xbfb8aa3b, v15
	v_mul_f32_e32 v175, 0xbfb8aa3b, v16
	v_exp_f32_e32 v185, v179
	v_exp_f32_e32 v197, v202
	v_exp_f32_e32 v203, v198
	v_lshl_add_u64 v[50:51], v[142:143], 0, v[66:67]
	v_rcp_f32_e32 v152, v154
	v_add_f32_e32 v161, 1.0, v160
	v_exp_f32_e32 v170, v173
	v_exp_f32_e32 v172, v175
	global_store_dwordx4 v[50:51], v[58:61], off
	v_mul_f32_e32 v38, v39, v171
	v_rcp_f32_e32 v163, v161
	v_add_u32_e32 v50, 0x90, v144
	v_mul_f32_e32 v166, v38, v35
	v_mul_f32_e32 v183, v41, v178
	v_ashrrev_i32_e32 v51, 31, v50
	v_mul_f32_e32 v35, v183, v37
	v_mul_f32_e32 v201, v22, v206
	v_add_f32_e32 v188, 1.0, v181
	v_lshlrev_b64 v[50:51], 8, v[50:51]
	v_cvt_pk_bf16_f32 v45, v34, v35
	v_mul_f32_e32 v208, v201, v18
	v_mul_f32_e32 v158, v24, v157
	v_rcp_f32_e32 v190, v188
	v_add_f32_e32 v194, 1.0, v193
	v_cvt_pk_bf16_f32 v44, v165, v166
	v_lshl_add_u64 v[34:35], v[142:143], 0, v[50:51]
	v_mul_f32_e32 v18, v158, v20
	v_add_f32_e32 v171, 1.0, v164
	v_add_f32_e32 v180, 1.0, v185
	v_rcp_f32_e32 v199, v194
	v_add_f32_e32 v205, 1.0, v197
	v_add_f32_e32 v200, 1.0, v203
	global_store_dwordx4 v[34:35], v[42:45], off
	v_mul_f32_e32 v22, v23, v152
	v_rcp_f32_e32 v20, v171
	v_add_f32_e32 v169, 1.0, v170
	v_add_f32_e32 v177, 1.0, v172
	v_rcp_f32_e32 v187, v180
	v_rcp_f32_e32 v204, v205
	v_rcp_f32_e32 v206, v200
	v_add_u32_e32 v34, 0xa0, v144
	v_mul_f32_e32 v209, v22, v19
	v_mul_f32_e32 v168, v25, v163
	v_rcp_f32_e32 v176, v169
	v_rcp_f32_e32 v182, v177
	v_ashrrev_i32_e32 v35, 31, v34
	v_mul_f32_e32 v19, v168, v21
	v_lshlrev_b64 v[34:35], 8, v[34:35]
	v_cvt_pk_bf16_f32 v29, v18, v19
	v_cvt_pk_bf16_f32 v28, v208, v209
	v_lshl_add_u64 v[18:19], v[142:143], 0, v[34:35]
	v_mul_f32_e32 v186, v6, v190
	global_store_dwordx4 v[18:19], v[26:29], off
	v_mul_f32_e32 v6, v7, v199
	v_mul_f32_e32 v165, v14, v20
	v_add_u32_e32 v18, 0xb0, v144
	v_mul_f32_e32 v184, v17, v187
	v_mul_f32_e32 v192, v186, v2
	v_mul_f32_e32 v195, v6, v3
	v_mul_f32_e32 v201, v8, v204
	v_mul_f32_e32 v153, v9, v206
	v_ashrrev_i32_e32 v19, 31, v18
	v_mul_f32_e32 v14, v15, v176
	v_mul_f32_e32 v178, v16, v182
	v_mul_f32_e32 v189, v184, v13
	v_mul_f32_e32 v2, v201, v4
	v_mul_f32_e32 v3, v153, v5
	v_mul_f32_e32 v166, v165, v10
	v_lshlrev_b64 v[18:19], 8, v[18:19]
	v_mul_f32_e32 v174, v14, v11
	v_mul_f32_e32 v183, v178, v12
	v_cvt_pk_bf16_f32 v13, v2, v3
	v_cvt_pk_bf16_f32 v10, v166, v174
	v_cvt_pk_bf16_f32 v11, v183, v189
	v_cvt_pk_bf16_f32 v12, v192, v195
	v_lshl_add_u64 v[2:3], v[142:143], 0, v[18:19]
	s_mov_b64 s[60:61], -1
	s_andn2_b64 vcc, exec, s[14:15]
	global_store_dwordx4 v[2:3], v[10:13], off
	s_cbranch_vccnz .LBB0_1122
	s_andn2_b64 vcc, exec, s[4:5]
	s_cbranch_vccnz .LBB0_1121
	s_barrier
	s_branch .LBB0_1121
